# GEMM0 end-of-tile barrier no longer drains the epilogue stores (only LDS reads)
# baseline (speedup 1.0000x reference)
; template <int MODE>
; DI void gemm_phase(const Params& p, int layer, unsigned char* lds) {
;     ...
;   for (int li = start; li < total; li += stride) {
;     ...
;         asm volatile("s_waitcnt lgkmcnt(0)" ::: "memory");
;       }
;     }
;     __syncthreads();
;   }
.LBB0_342:
	s_waitcnt lgkmcnt(0)
	v_add_u32_e32 v128, v128, v143
	v_cmp_ge_i32_e32 vcc, v128, v129
	s_or_b64 s[36:37], vcc, s[36:37]
	s_waitcnt lgkmcnt(0)
	s_barrier
	s_andn2_b64 exec, exec, s[36:37]
	s_cbranch_execz .LBB0_357
